# attention combine: the 16 exchange-tile LDS reads issued together (renamed registers, counted lgkmcnt) on top of v162 (gain loads hoisted, full-line output stores through LDS)
# baseline (speedup 1.0000x reference)
.LBB0_1137:
	s_waitcnt lgkmcnt(0)
	s_barrier
	s_andn2_b64 vcc, exec, s[16:17]
	s_cbranch_vccnz .LBB0_1115
	v_div_scale_f32 v3, s[0:1], v2, v2, 1.0
	v_rcp_f32_e32 v84, v3
	v_div_scale_f32 v86, vcc, 1.0, v2, 1.0
	s_lshl_b32 s50, s90, 9
	v_fma_f32 v87, -v3, v84, 1.0
	v_fmac_f32_e32 v84, v87, v84
	v_mul_f32_e32 v90, v86, v84
	v_fma_f32 v87, -v3, v90, v86
	v_fmac_f32_e32 v90, v87, v84
	v_fma_f32 v3, -v3, v90, v86
	v_div_fmas_f32 v3, v3, v84, v90
	ds_read_b128 v[166:169], v152
	ds_read_b128 v[170:173], v152 offset:1024
	ds_read_b128 v[174:177], v152 offset:2048
	ds_read_b128 v[178:181], v152 offset:3072
	ds_read_b128 v[182:185], v152 offset:4096
	ds_read_b128 v[186:189], v152 offset:5120
	ds_read_b128 v[190:193], v152 offset:6144
	ds_read_b128 v[194:197], v152 offset:7168
	ds_read_b128 v[198:201], v152 offset:8192
	ds_read_b128 v[202:205], v152 offset:9216
	ds_read_b128 v[206:209], v152 offset:10240
	ds_read_b128 v[210:213], v152 offset:11264
	ds_read_b128 v[214:217], v152 offset:12288
	ds_read_b128 v[218:221], v152 offset:13312
	ds_read_b128 v[86:89], v152 offset:14336
	ds_read_b128 v[90:93], v152 offset:15360
	v_div_fixup_f32 v84, v3, v2, 1.0
	v_mov_b32_e32 v145, v0
	s_waitcnt lgkmcnt(14)
	v_xor_b32_e32 v3, 0x80000000, v169
	v_xor_b32_e32 v2, 0x80000000, v168
	v_pk_fma_f32 v[80:81], v[80:81], v[84:85], v[166:167] op_sel_hi:[1,0,1] neg_lo:[0,0,1] neg_hi:[0,0,1]
	v_pk_fma_f32 v[82:83], v[82:83], v[84:85], v[2:3] op_sel_hi:[1,0,1]
	v_pk_mul_f32 v[166:167], v[80:81], v[80:81]
	v_pk_mul_f32 v[2:3], v[82:83], v[82:83]
	s_nop 0
	v_pk_mov_b32 v[168:169], v[166:167], v[2:3] op_sel:[1,0]
	v_mov_b32_e32 v167, v3
	v_pk_fma_f32 v[2:3], v[76:77], v[84:85], v[170:171] op_sel_hi:[1,0,1] neg_lo:[0,0,1] neg_hi:[0,0,1]
	v_xor_b32_e32 v77, 0x80000000, v173
	v_xor_b32_e32 v76, 0x80000000, v172
	v_pk_fma_f32 v[76:77], v[78:79], v[84:85], v[76:77] op_sel_hi:[1,0,1]
	v_pk_mul_f32 v[170:171], v[2:3], v[2:3]
	v_pk_mul_f32 v[78:79], v[76:77], v[76:77]
	v_pk_add_f32 v[94:95], v[168:169], v[166:167]
	v_pk_mov_b32 v[172:173], v[170:171], v[78:79] op_sel:[1,0]
	v_mov_b32_e32 v171, v79
	v_pk_add_f32 v[78:79], v[172:173], v[170:171]
	v_pk_add_f32 v[78:79], v[78:79], v[78:79] op_sel:[0,1] op_sel_hi:[1,0]
	s_waitcnt lgkmcnt(12)
	v_xor_b32_e32 v177, 0x80000000, v177
	v_xor_b32_e32 v176, 0x80000000, v176
	v_pk_fma_f32 v[72:73], v[72:73], v[84:85], v[174:175] op_sel_hi:[1,0,1] neg_lo:[0,0,1] neg_hi:[0,0,1]
	v_xor_b32_e32 v175, 0x80000000, v181
	v_xor_b32_e32 v174, 0x80000000, v180
	v_pk_fma_f32 v[68:69], v[68:69], v[84:85], v[178:179] op_sel_hi:[1,0,1] neg_lo:[0,0,1] neg_hi:[0,0,1]
	v_pk_fma_f32 v[74:75], v[74:75], v[84:85], v[176:177] op_sel_hi:[1,0,1]
	v_pk_fma_f32 v[70:71], v[70:71], v[84:85], v[174:175] op_sel_hi:[1,0,1]
	v_mul_f32_e32 v176, v68, v68
	v_mul_f32_e32 v177, v69, v69
	v_pk_add_f32 v[174:175], v[94:95], v[94:95] op_sel:[0,1] op_sel_hi:[1,0]
	v_mov_b32_e32 v79, v177
	v_mov_b32_e32 v175, v176
	v_pk_add_f32 v[78:79], v[174:175], v[78:79]
	v_mul_f32_e32 v174, v73, v73
	v_mul_f32_e32 v180, v70, v70
	v_pk_fma_f32 v[178:179], v[72:73], v[72:73], v[174:175] op_sel_hi:[1,1,0]
	v_mul_f32_e32 v174, v75, v75
	v_mov_b32_e32 v179, v180
	v_pk_fma_f32 v[180:181], v[74:75], v[74:75], v[174:175] op_sel_hi:[1,1,0]
	v_mul_f32_e32 v96, v71, v71
	v_mov_b32_e32 v181, v96
	v_pk_add_f32 v[178:179], v[178:179], v[180:181]
	s_nop 0
	v_pk_add_f32 v[78:79], v[78:79], v[178:179]
	s_waitcnt lgkmcnt(10)
	v_pk_fma_f32 v[64:65], v[64:65], v[84:85], v[182:183] op_sel_hi:[1,0,1] neg_lo:[0,0,1] neg_hi:[0,0,1]
	v_xor_b32_e32 v183, 0x80000000, v185
	v_xor_b32_e32 v182, 0x80000000, v184
	v_pk_fma_f32 v[66:67], v[66:67], v[84:85], v[182:183] op_sel_hi:[1,0,1]
	v_pk_mul_f32 v[184:185], v[64:65], v[64:65]
	v_pk_mul_f32 v[182:183], v[66:67], v[66:67]
	v_xor_b32_e32 v189, 0x80000000, v189
	v_pk_mov_b32 v[94:95], v[184:185], v[182:183] op_sel:[1,0]
	v_mov_b32_e32 v185, v183
	v_pk_add_f32 v[94:95], v[94:95], v[184:185]
	v_xor_b32_e32 v188, 0x80000000, v188
	v_pk_fma_f32 v[62:63], v[62:63], v[84:85], v[188:189] op_sel_hi:[1,0,1]
	v_pk_fma_f32 v[60:61], v[60:61], v[84:85], v[186:187] op_sel_hi:[1,0,1] neg_lo:[0,0,1] neg_hi:[0,0,1]
	s_waitcnt lgkmcnt(8)
	v_pk_fma_f32 v[56:57], v[56:57], v[84:85], v[190:191] op_sel_hi:[1,0,1] neg_lo:[0,0,1] neg_hi:[0,0,1]
	v_xor_b32_e32 v193, 0x80000000, v193
	v_xor_b32_e32 v192, 0x80000000, v192
	v_mul_f32_e32 v190, v56, v56
	v_pk_add_f32 v[78:79], v[78:79], v[78:79] op_sel:[0,1] op_sel_hi:[1,0]
	v_pk_fma_f32 v[58:59], v[58:59], v[84:85], v[192:193] op_sel_hi:[1,0,1]
	v_mul_f32_e32 v192, v57, v57
	v_mov_b32_e32 v79, v190
	v_pk_add_f32 v[190:191], v[94:95], v[94:95] op_sel:[0,1] op_sel_hi:[1,0]
	v_mul_f32_e32 v193, v58, v58
	v_mov_b32_e32 v191, v192
	v_pk_add_f32 v[78:79], v[78:79], v[190:191]
	v_mul_f32_e32 v190, v61, v61
	v_pk_fma_f32 v[190:191], v[60:61], v[60:61], v[190:191] op_sel_hi:[1,1,0]
	v_mul_f32_e32 v192, v63, v63
	v_mul_f32_e32 v96, v59, v59
	v_mov_b32_e32 v191, v193
	v_pk_fma_f32 v[192:193], v[62:63], v[62:63], v[192:193] op_sel_hi:[1,1,0]
	v_pk_fma_f32 v[52:53], v[52:53], v[84:85], v[194:195] op_sel_hi:[1,0,1] neg_lo:[0,0,1] neg_hi:[0,0,1]
	v_mov_b32_e32 v193, v96
	v_pk_add_f32 v[190:191], v[190:191], v[192:193]
	s_nop 0
	v_pk_add_f32 v[78:79], v[78:79], v[190:191]
	v_xor_b32_e32 v191, 0x80000000, v197
	v_xor_b32_e32 v190, 0x80000000, v196
	v_pk_fma_f32 v[54:55], v[54:55], v[84:85], v[190:191] op_sel_hi:[1,0,1]
	v_pk_mul_f32 v[196:197], v[52:53], v[52:53]
	v_pk_mul_f32 v[194:195], v[54:55], v[54:55]
	v_pk_mov_b32 v[94:95], v[196:197], v[194:195] op_sel:[1,0]
	v_mov_b32_e32 v197, v195
	v_pk_add_f32 v[94:95], v[94:95], v[196:197]
	s_waitcnt lgkmcnt(6)
	v_pk_fma_f32 v[48:49], v[48:49], v[84:85], v[198:199] op_sel_hi:[1,0,1] neg_lo:[0,0,1] neg_hi:[0,0,1]
	v_xor_b32_e32 v201, 0x80000000, v201
	v_xor_b32_e32 v200, 0x80000000, v200
	v_pk_add_f32 v[78:79], v[78:79], v[78:79] op_sel:[0,1] op_sel_hi:[1,0]
	v_xor_b32_e32 v199, 0x80000000, v205
	v_xor_b32_e32 v198, 0x80000000, v204
	v_pk_fma_f32 v[44:45], v[44:45], v[84:85], v[202:203] op_sel_hi:[1,0,1] neg_lo:[0,0,1] neg_hi:[0,0,1]
	v_pk_fma_f32 v[46:47], v[46:47], v[84:85], v[198:199] op_sel_hi:[1,0,1]
	v_mul_f32_e32 v198, v44, v44
	v_pk_fma_f32 v[50:51], v[50:51], v[84:85], v[200:201] op_sel_hi:[1,0,1]
	v_mul_f32_e32 v200, v45, v45
	v_mov_b32_e32 v79, v198
	v_pk_add_f32 v[198:199], v[94:95], v[94:95] op_sel:[0,1] op_sel_hi:[1,0]
	v_mul_f32_e32 v201, v46, v46
	v_mov_b32_e32 v199, v200
	v_pk_add_f32 v[78:79], v[78:79], v[198:199]
	v_mul_f32_e32 v198, v49, v49
	v_pk_fma_f32 v[202:203], v[48:49], v[48:49], v[198:199] op_sel_hi:[1,1,0]
	v_mul_f32_e32 v198, v51, v51
	v_mov_b32_e32 v203, v201
	v_pk_fma_f32 v[204:205], v[50:51], v[50:51], v[198:199] op_sel_hi:[1,1,0]
	v_mul_f32_e32 v96, v47, v47
	v_mov_b32_e32 v205, v96
	v_pk_add_f32 v[202:203], v[202:203], v[204:205]
	s_nop 0
	v_pk_add_f32 v[78:79], v[78:79], v[202:203]
	s_waitcnt lgkmcnt(4)
	v_pk_fma_f32 v[40:41], v[40:41], v[84:85], v[206:207] op_sel_hi:[1,0,1] neg_lo:[0,0,1] neg_hi:[0,0,1]
	v_xor_b32_e32 v207, 0x80000000, v209
	v_xor_b32_e32 v206, 0x80000000, v208
	v_pk_fma_f32 v[42:43], v[42:43], v[84:85], v[206:207] op_sel_hi:[1,0,1]
	v_pk_mul_f32 v[208:209], v[40:41], v[40:41]
	v_pk_mul_f32 v[206:207], v[42:43], v[42:43]
	v_xor_b32_e32 v213, 0x80000000, v213
	v_pk_mov_b32 v[94:95], v[208:209], v[206:207] op_sel:[1,0]
	v_mov_b32_e32 v209, v207
	v_pk_add_f32 v[94:95], v[94:95], v[208:209]
	v_xor_b32_e32 v212, 0x80000000, v212
	v_pk_fma_f32 v[38:39], v[38:39], v[84:85], v[212:213] op_sel_hi:[1,0,1]
	v_pk_fma_f32 v[36:37], v[36:37], v[84:85], v[210:211] op_sel_hi:[1,0,1] neg_lo:[0,0,1] neg_hi:[0,0,1]
	s_waitcnt lgkmcnt(2)
	v_pk_fma_f32 v[32:33], v[32:33], v[84:85], v[214:215] op_sel_hi:[1,0,1] neg_lo:[0,0,1] neg_hi:[0,0,1]
	v_xor_b32_e32 v217, 0x80000000, v217
	v_xor_b32_e32 v216, 0x80000000, v216
	v_mul_f32_e32 v214, v32, v32
	v_pk_add_f32 v[78:79], v[78:79], v[78:79] op_sel:[0,1] op_sel_hi:[1,0]
	v_pk_fma_f32 v[34:35], v[34:35], v[84:85], v[216:217] op_sel_hi:[1,0,1]
	v_mul_f32_e32 v216, v33, v33
	v_mov_b32_e32 v79, v214
	v_pk_add_f32 v[214:215], v[94:95], v[94:95] op_sel:[0,1] op_sel_hi:[1,0]
	v_mul_f32_e32 v217, v34, v34
	v_mov_b32_e32 v215, v216
	v_pk_add_f32 v[78:79], v[78:79], v[214:215]
	v_mul_f32_e32 v214, v37, v37
	v_pk_fma_f32 v[214:215], v[36:37], v[36:37], v[214:215] op_sel_hi:[1,1,0]
	v_mul_f32_e32 v216, v39, v39
	v_mul_f32_e32 v96, v35, v35
	v_mov_b32_e32 v215, v217
	v_pk_fma_f32 v[216:217], v[38:39], v[38:39], v[216:217] op_sel_hi:[1,1,0]
	v_pk_fma_f32 v[28:29], v[28:29], v[84:85], v[218:219] op_sel_hi:[1,0,1] neg_lo:[0,0,1] neg_hi:[0,0,1]
	v_mov_b32_e32 v217, v96
	v_pk_add_f32 v[214:215], v[214:215], v[216:217]
	s_nop 0
	v_pk_add_f32 v[78:79], v[78:79], v[214:215]
	v_xor_b32_e32 v215, 0x80000000, v221
	v_xor_b32_e32 v214, 0x80000000, v220
	v_pk_fma_f32 v[30:31], v[30:31], v[84:85], v[214:215] op_sel_hi:[1,0,1]
	v_pk_mul_f32 v[218:219], v[30:31], v[30:31]
	v_pk_mul_f32 v[220:221], v[28:29], v[28:29]
	v_pk_add_f32 v[78:79], v[78:79], v[78:79] op_sel:[0,1] op_sel_hi:[1,0]
	v_pk_mov_b32 v[94:95], v[220:221], v[218:219] op_sel:[1,0]
	v_mov_b32_e32 v221, v219
	v_pk_add_f32 v[94:95], v[94:95], v[220:221]
	s_waitcnt lgkmcnt(0)
	v_xor_b32_e32 v89, 0x80000000, v89
	v_xor_b32_e32 v88, 0x80000000, v88
	v_pk_fma_f32 v[26:27], v[26:27], v[84:85], v[88:89] op_sel_hi:[1,0,1]
	v_pk_fma_f32 v[24:25], v[24:25], v[84:85], v[86:87] op_sel_hi:[1,0,1] neg_lo:[0,0,1] neg_hi:[0,0,1]
	global_load_dwordx4 v[86:89], v[136:137], off
	global_load_dwordx4 v[166:169], v[136:137], off offset:64
	global_load_dwordx4 v[170:173], v[136:137], off offset:128
	global_load_dwordx4 v[174:177], v[136:137], off offset:192
	global_load_dwordx4 v[178:181], v[136:137], off offset:256
	global_load_dwordx4 v[182:185], v[136:137], off offset:320
	global_load_dwordx4 v[186:189], v[136:137], off offset:384
	global_load_dwordx4 v[190:193], v[136:137], off offset:448
	global_load_dwordx4 v[194:197], v[136:137], off offset:512
	global_load_dwordx4 v[198:201], v[136:137], off offset:576
	global_load_dwordx4 v[202:205], v[136:137], off offset:640
	global_load_dwordx4 v[206:209], v[136:137], off offset:704
	global_load_dwordx4 v[210:213], v[136:137], off offset:768
	global_load_dwordx4 v[214:217], v[136:137], off offset:832
	global_load_dwordx4 v[218:221], v[136:137], off offset:896
	global_load_dwordx4 v[222:225], v[136:137], off offset:960
	v_xor_b32_e32 v93, 0x80000000, v93
	v_xor_b32_e32 v92, 0x80000000, v92
	v_pk_fma_f32 v[20:21], v[20:21], v[84:85], v[90:91] op_sel_hi:[1,0,1] neg_lo:[0,0,1] neg_hi:[0,0,1]
	v_pk_fma_f32 v[22:23], v[22:23], v[84:85], v[92:93] op_sel_hi:[1,0,1]
	v_mul_f32_e32 v84, v20, v20
	v_mul_f32_e32 v92, v21, v21
	v_pk_add_f32 v[90:91], v[94:95], v[94:95] op_sel:[0,1] op_sel_hi:[1,0]
	v_mov_b32_e32 v79, v84
	v_mov_b32_e32 v91, v92
	v_mul_f32_e32 v84, v25, v25
	v_mul_f32_e32 v93, v22, v22
	v_pk_add_f32 v[78:79], v[78:79], v[90:91]
	v_pk_fma_f32 v[90:91], v[24:25], v[24:25], v[84:85] op_sel_hi:[1,1,0]
	v_mul_f32_e32 v84, v27, v27
	v_mul_f32_e32 v96, v23, v23
	v_mov_b32_e32 v91, v93
	v_pk_fma_f32 v[92:93], v[26:27], v[26:27], v[84:85] op_sel_hi:[1,1,0]
	s_waitcnt vmcnt(0)
	v_pk_mul_f32 v[80:81], v[80:81], v[86:87]
	v_mov_b32_e32 v93, v96
	v_pk_add_f32 v[90:91], v[90:91], v[92:93]
	v_pk_mul_f32 v[82:83], v[82:83], v[88:89]
	v_pk_add_f32 v[78:79], v[78:79], v[90:91]
	s_nop 0
	v_add_f32_e32 v78, v78, v79
	ds_bpermute_b32 v1, v1, v78
	s_waitcnt lgkmcnt(0)
	v_add_f32_e32 v1, v78, v1
	ds_bpermute_b32 v78, v85, v1
	s_waitcnt lgkmcnt(0)
	v_add_f32_e32 v1, v1, v78
	v_fmamk_f32 v1, v1, 0x3b800000, v162
	v_mul_f32_e32 v78, 0x4f800000, v1
	v_cmp_gt_f32_e32 vcc, s88, v1
	s_nop 1
	v_cndmask_b32_e32 v1, v1, v78, vcc
	v_sqrt_f32_e32 v78, v1
	s_nop 0
	v_add_u32_e32 v79, -1, v78
	v_fma_f32 v84, -v79, v78, v1
	v_cmp_ge_f32_e64 s[0:1], 0, v84
	v_add_u32_e32 v84, 1, v78
	s_nop 0
	v_cndmask_b32_e64 v79, v78, v79, s[0:1]
	v_fma_f32 v78, -v84, v78, v1
	v_cmp_lt_f32_e64 s[0:1], 0, v78
	s_nop 1
	v_cndmask_b32_e64 v78, v79, v84, s[0:1]
	v_mul_f32_e32 v79, 0x37800000, v78
	v_cndmask_b32_e32 v78, v78, v79, vcc
	v_cmp_class_f32_e32 vcc, v1, v163
	s_nop 1
	v_cndmask_b32_e32 v1, v78, v1, vcc
	v_div_scale_f32 v78, s[0:1], v1, v1, s89
	v_rcp_f32_e32 v79, v78
	s_nop 0
	v_fma_f32 v84, -v78, v79, 1.0
	v_fmac_f32_e32 v79, v84, v79
	v_div_scale_f32 v84, vcc, s89, v1, s89
	v_mul_f32_e32 v85, v84, v79
	v_fma_f32 v90, -v78, v85, v84
	v_fmac_f32_e32 v85, v90, v79
	v_fma_f32 v78, -v78, v85, v84
	v_div_fmas_f32 v78, v78, v79, v85
	v_div_fixup_f32 v84, v78, v1, s89
	v_lshrrev_b32_e32 v78, 5, v227
	v_mul_u32_u24_e32 v96, 0x210, v78
	v_add_u32_e32 v78, s91, v78
	v_mov_b32_e32 v79, v0
	v_lshlrev_b64 v[78:79], 12, v[78:79]
	v_lshl_add_u64 v[78:79], s[4:5], 0, v[78:79]
	v_lshl_add_u64 v[78:79], v[78:79], 0, s[50:51]
	v_and_b32_e32 v98, 31, v227
	v_lshlrev_b32_e32 v98, 4, v98
	v_mov_b32_e32 v99, v0
	v_add_u32_e32 v96, v96, v98
	v_lshlrev_b32_e32 v100, 4, v227
	v_sub_u32_e32 v100, v152, v100
	v_add_u32_e32 v96, v100, v96
	v_lshl_add_u64 v[78:79], v[78:79], 0, v[98:99]
	v_and_b32_e32 v97, 15, v227
	v_mul_u32_u24_e32 v97, 0x210, v97
	v_lshrrev_b32_e32 v98, 4, v227
	v_lshl_add_u32 v97, v98, 3, v97
	v_add_u32_e32 v97, v100, v97
	v_pk_mul_f32 v[80:81], v[80:81], v[84:85] op_sel_hi:[1,0]
	v_pk_mul_f32 v[82:83], v[82:83], v[84:85] op_sel_hi:[1,0]
	v_cvt_pk_bf16_f32 v80, v80, v81
	s_nop 0
	v_cvt_pk_bf16_f32 v81, v82, v83
	ds_write_b64 v97, v[80:81]
	v_pk_mul_f32 v[2:3], v[2:3], v[166:167]
	v_pk_mul_f32 v[76:77], v[76:77], v[168:169]
	v_pk_mul_f32 v[2:3], v[2:3], v[84:85] op_sel_hi:[1,0]
	v_pk_mul_f32 v[76:77], v[76:77], v[84:85] op_sel_hi:[1,0]
	v_cvt_pk_bf16_f32 v2, v2, v3
	s_nop 0
	v_cvt_pk_bf16_f32 v3, v76, v77
	ds_write_b64 v97, v[2:3] offset:32
	v_pk_mul_f32 v[2:3], v[72:73], v[170:171]
	v_pk_mul_f32 v[72:73], v[74:75], v[172:173]
	v_pk_mul_f32 v[2:3], v[2:3], v[84:85] op_sel_hi:[1,0]
	v_pk_mul_f32 v[72:73], v[72:73], v[84:85] op_sel_hi:[1,0]
	v_cvt_pk_bf16_f32 v2, v2, v3
	s_nop 0
	v_cvt_pk_bf16_f32 v3, v72, v73
	ds_write_b64 v97, v[2:3] offset:64
	v_pk_mul_f32 v[2:3], v[68:69], v[174:175]
	v_pk_mul_f32 v[68:69], v[70:71], v[176:177]
	v_pk_mul_f32 v[2:3], v[84:85], v[2:3] op_sel_hi:[0,1]
	v_pk_mul_f32 v[68:69], v[84:85], v[68:69] op_sel_hi:[0,1]
	v_cvt_pk_bf16_f32 v2, v2, v3
	v_cvt_pk_bf16_f32 v3, v68, v69
	ds_write_b64 v97, v[2:3] offset:96
	v_pk_mul_f32 v[2:3], v[64:65], v[178:179]
	v_pk_mul_f32 v[64:65], v[66:67], v[180:181]
	v_pk_mul_f32 v[2:3], v[84:85], v[2:3] op_sel_hi:[0,1]
	v_pk_mul_f32 v[64:65], v[84:85], v[64:65] op_sel_hi:[0,1]
	v_cvt_pk_bf16_f32 v2, v2, v3
	v_cvt_pk_bf16_f32 v3, v64, v65
	ds_write_b64 v97, v[2:3] offset:128
	v_pk_mul_f32 v[2:3], v[60:61], v[182:183]
	v_pk_mul_f32 v[60:61], v[62:63], v[184:185]
	v_pk_mul_f32 v[2:3], v[84:85], v[2:3] op_sel_hi:[0,1]
	v_pk_mul_f32 v[60:61], v[84:85], v[60:61] op_sel_hi:[0,1]
	v_cvt_pk_bf16_f32 v2, v2, v3
	v_cvt_pk_bf16_f32 v3, v60, v61
	ds_write_b64 v97, v[2:3] offset:160
	v_pk_mul_f32 v[2:3], v[56:57], v[186:187]
	v_pk_mul_f32 v[56:57], v[58:59], v[188:189]
	v_pk_mul_f32 v[2:3], v[84:85], v[2:3] op_sel_hi:[0,1]
	v_pk_mul_f32 v[56:57], v[84:85], v[56:57] op_sel_hi:[0,1]
	v_cvt_pk_bf16_f32 v2, v2, v3
	v_cvt_pk_bf16_f32 v3, v56, v57
	ds_write_b64 v97, v[2:3] offset:192
	v_pk_mul_f32 v[2:3], v[52:53], v[190:191]
	v_pk_mul_f32 v[52:53], v[54:55], v[192:193]
	v_pk_mul_f32 v[2:3], v[84:85], v[2:3] op_sel_hi:[0,1]
	v_pk_mul_f32 v[52:53], v[84:85], v[52:53] op_sel_hi:[0,1]
	v_cvt_pk_bf16_f32 v2, v2, v3
	v_cvt_pk_bf16_f32 v3, v52, v53
	ds_write_b64 v97, v[2:3] offset:224
	v_pk_mul_f32 v[2:3], v[48:49], v[194:195]
	v_pk_mul_f32 v[48:49], v[50:51], v[196:197]
	v_pk_mul_f32 v[2:3], v[84:85], v[2:3] op_sel_hi:[0,1]
	v_pk_mul_f32 v[48:49], v[84:85], v[48:49] op_sel_hi:[0,1]
	v_cvt_pk_bf16_f32 v2, v2, v3
	v_cvt_pk_bf16_f32 v3, v48, v49
	ds_write_b64 v97, v[2:3] offset:256
	v_pk_mul_f32 v[2:3], v[44:45], v[198:199]
	v_pk_mul_f32 v[44:45], v[46:47], v[200:201]
	v_pk_mul_f32 v[2:3], v[84:85], v[2:3] op_sel_hi:[0,1]
	v_pk_mul_f32 v[44:45], v[84:85], v[44:45] op_sel_hi:[0,1]
	v_cvt_pk_bf16_f32 v2, v2, v3
	v_cvt_pk_bf16_f32 v3, v44, v45
	ds_write_b64 v97, v[2:3] offset:288
	v_pk_mul_f32 v[2:3], v[40:41], v[202:203]
	v_pk_mul_f32 v[40:41], v[42:43], v[204:205]
	v_pk_mul_f32 v[2:3], v[84:85], v[2:3] op_sel_hi:[0,1]
	v_pk_mul_f32 v[40:41], v[84:85], v[40:41] op_sel_hi:[0,1]
	v_cvt_pk_bf16_f32 v2, v2, v3
	v_cvt_pk_bf16_f32 v3, v40, v41
	ds_write_b64 v97, v[2:3] offset:320
	v_pk_mul_f32 v[2:3], v[36:37], v[206:207]
	v_pk_mul_f32 v[36:37], v[38:39], v[208:209]
	v_pk_mul_f32 v[2:3], v[84:85], v[2:3] op_sel_hi:[0,1]
	v_pk_mul_f32 v[36:37], v[84:85], v[36:37] op_sel_hi:[0,1]
	v_cvt_pk_bf16_f32 v2, v2, v3
	v_cvt_pk_bf16_f32 v3, v36, v37
	ds_write_b64 v97, v[2:3] offset:352
	v_pk_mul_f32 v[2:3], v[32:33], v[210:211]
	v_pk_mul_f32 v[32:33], v[34:35], v[212:213]
	v_pk_mul_f32 v[2:3], v[84:85], v[2:3] op_sel_hi:[0,1]
	v_pk_mul_f32 v[32:33], v[84:85], v[32:33] op_sel_hi:[0,1]
	v_cvt_pk_bf16_f32 v2, v2, v3
	v_cvt_pk_bf16_f32 v3, v32, v33
	ds_write_b64 v97, v[2:3] offset:384
	v_pk_mul_f32 v[2:3], v[28:29], v[214:215]
	v_pk_mul_f32 v[28:29], v[30:31], v[216:217]
	v_pk_mul_f32 v[2:3], v[84:85], v[2:3] op_sel_hi:[0,1]
	v_pk_mul_f32 v[28:29], v[84:85], v[28:29] op_sel_hi:[0,1]
	v_cvt_pk_bf16_f32 v2, v2, v3
	v_cvt_pk_bf16_f32 v3, v28, v29
	ds_write_b64 v97, v[2:3] offset:416
	v_pk_mul_f32 v[2:3], v[24:25], v[218:219]
	v_pk_mul_f32 v[24:25], v[26:27], v[220:221]
	v_pk_mul_f32 v[2:3], v[84:85], v[2:3] op_sel_hi:[0,1]
	v_pk_mul_f32 v[24:25], v[84:85], v[24:25] op_sel_hi:[0,1]
	v_cvt_pk_bf16_f32 v2, v2, v3
	v_cvt_pk_bf16_f32 v3, v24, v25
	ds_write_b64 v97, v[2:3] offset:448
	v_pk_mul_f32 v[2:3], v[20:21], v[222:223]
	v_pk_mul_f32 v[20:21], v[22:23], v[224:225]
	v_pk_mul_f32 v[2:3], v[84:85], v[2:3] op_sel_hi:[0,1]
	v_pk_mul_f32 v[20:21], v[84:85], v[20:21] op_sel_hi:[0,1]
	v_cvt_pk_bf16_f32 v2, v2, v3
	v_cvt_pk_bf16_f32 v3, v20, v21
	ds_write_b64 v97, v[2:3] offset:480
	s_mov_b32 s0, 0x2000
	s_mov_b32 s1, 0
	s_waitcnt lgkmcnt(0)
	ds_read_b128 v[98:101], v96
	ds_read_b128 v[102:105], v96 offset:1056
	ds_read_b128 v[106:109], v96 offset:2112
	ds_read_b128 v[110:113], v96 offset:3168
	ds_read_b128 v[114:117], v96 offset:4224
	ds_read_b128 v[118:121], v96 offset:5280
	ds_read_b128 v[122:125], v96 offset:6336
	ds_read_b128 v[126:129], v96 offset:7392
	s_waitcnt lgkmcnt(7)
	global_store_dwordx4 v[78:79], v[98:101], off
	v_lshl_add_u64 v[78:79], v[78:79], 0, s[0:1]
	s_waitcnt lgkmcnt(6)
	global_store_dwordx4 v[78:79], v[102:105], off
	v_lshl_add_u64 v[78:79], v[78:79], 0, s[0:1]
	s_waitcnt lgkmcnt(5)
	global_store_dwordx4 v[78:79], v[106:109], off
	v_lshl_add_u64 v[78:79], v[78:79], 0, s[0:1]
	s_waitcnt lgkmcnt(4)
	global_store_dwordx4 v[78:79], v[110:113], off
	v_lshl_add_u64 v[78:79], v[78:79], 0, s[0:1]
	s_waitcnt lgkmcnt(3)
	global_store_dwordx4 v[78:79], v[114:117], off
	v_lshl_add_u64 v[78:79], v[78:79], 0, s[0:1]
	s_waitcnt lgkmcnt(2)
	global_store_dwordx4 v[78:79], v[118:121], off
	v_lshl_add_u64 v[78:79], v[78:79], 0, s[0:1]
	s_waitcnt lgkmcnt(1)
	global_store_dwordx4 v[78:79], v[122:125], off
	v_lshl_add_u64 v[78:79], v[78:79], 0, s[0:1]
	s_waitcnt lgkmcnt(0)
	global_store_dwordx4 v[78:79], v[126:129], off
	s_branch .LBB0_1115
